# rowpass layers 0-2: last row round reassigned from the context-row-owning workgroups to the others (on v14)
# baseline (speedup 1.0000x reference)
; DI void rowpass(const Params& p, int l, bool first, int wv, char* smem) {
;     ...
;   for (int R = blockIdx.x * 8 + w; R < NTOK; R += gridDim.x * 8) {
.LBB0_103:
	v_readlane_b32 s0, v253, 56
	s_and_b64 vcc, exec, s[4:5]
	s_cbranch_vccnz .Lrb_old
	s_cmpk_lg_i32 s0, 0x800
	s_cbranch_scc1 .Lrb_old
	s_cmpk_gt_i32 s6, 0x1fff
	s_cbranch_scc1 .LBB0_117
	s_cmpk_lt_i32 s6, 0x1800
	s_cbranch_scc1 .Lrb_old
	s_cmpk_lt_i32 s6, 0x1c00
	s_cbranch_scc1 .LBB0_117
	s_movk_i32 s0, 0x400
.Lrb_old:
	s_add_i32 s6, s6, s0
	s_cmpk_gt_i32 s6, 0x23ff
	s_cbranch_scc1 .LBB0_117

; DI void rowpass(const Params& p, int l, bool first, int wv, char* smem) {
;     ...
;   for (int R = blockIdx.x * 8 + w; R < NTOK; R += gridDim.x * 8) {
;     const int b = R / TPB, j = R - b * TPB;
;     const bool isctx = j < 256;
;     const int mr = isctx ? 4 : b;
;     if (!first && l == 3 && isctx) continue;
;     const float* hin; float* hout;
;     if (isctx) {
;       hout = p.hc + (size_t)(b * 256 + j) * DM;
;       hin = (first || l == 0) ? p.ctx + (size_t)(b * 256 + j) * DM : hout;
;     } else {
;       hout = p.out + (size_t)(b * 2048 + (j - 256)) * DM;
;       hin = (first || l == 0) ? p.x + (size_t)(b * 2048 + (j - 256)) * DM : hout;
;     }
;     f32x4 hv[8];
; #pragma unroll
;     for (int i = 0; i < 8; ++i) hv[i] = *(const f32x4*)(hin + i * 256 + lane * 4);
.LBB0_115:
	v_readlane_b32 s2, v253, 56
	s_and_b64 vcc, exec, s[4:5]
	s_cbranch_vccnz .Lrb_pold
	s_cmpk_lg_i32 s2, 0x800
	s_cbranch_scc1 .Lrb_pold
	s_cmpk_gt_i32 s6, 0x1fff
	s_cbranch_scc1 .Lrp_nopf
	s_cmpk_lt_i32 s6, 0x1800
	s_cbranch_scc1 .Lrb_pold
	s_cmpk_lt_i32 s6, 0x1c00
	s_cbranch_scc1 .Lrp_nopf
	s_movk_i32 s2, 0x400
.Lrb_pold:
	s_add_i32 s2, s6, s2
	s_cmpk_gt_i32 s2, 0x23ff
	s_cbranch_scc1 .Lrp_nopf
	s_mul_hi_i32 s3, s2, 0x38e38e39
	s_lshr_b32 s7, s3, 31
	s_ashr_i32 s3, s3, 9
	s_add_i32 s3, s3, s7
	s_mul_i32 s7, s3, 0xfffff700
	s_add_i32 s7, s7, s2
	s_cmpk_lt_i32 s7, 0x100
	s_cbranch_scc1 .Lrp_nopf
	s_lshl_b32 s3, s3, 8
	s_sub_i32 s3, s2, s3
	s_add_i32 s10, s3, 0xffffff00
	s_ashr_i32 s11, s10, 31
	s_lshl_b64 s[10:11], s[10:11], 13
	v_readlane_b32 s12, v254, 22
	v_readlane_b32 s13, v254, 23
	v_readlane_b32 s24, v253, 27
	v_readlane_b32 s21, v253, 28
	s_and_b64 vcc, s[8:9], exec
	s_cselect_b32 s12, s12, s24
	s_cselect_b32 s13, s13, s21
	s_add_u32 s12, s12, s10
	s_addc_u32 s13, s13, s11
	v_mov_b32_e32 v238, s12
	v_mov_b32_e32 v239, s13
	v_lshl_add_u64 v[238:239], v[130:131], 2, v[238:239]
	global_load_dwordx4 v[180:183], v[238:239], off
	global_load_dwordx4 v[184:187], v[238:239], off offset:1024
	global_load_dwordx4 v[188:191], v[238:239], off offset:2048
	global_load_dwordx4 v[192:195], v[238:239], off offset:3072
	s_mov_b64 s[10:11], 0x1000
	v_lshl_add_u64 v[238:239], v[238:239], 0, s[10:11]
	global_load_dwordx4 v[196:199], v[238:239], off
	global_load_dwordx4 v[200:203], v[238:239], off offset:1024
	global_load_dwordx4 v[204:207], v[238:239], off offset:2048
	global_load_dwordx4 v[208:211], v[238:239], off offset:3072
	s_ashr_i32 s3, s2, 31
	s_lshl_b64 s[10:11], s[2:3], 12
	v_lshl_add_u64 v[240:241], v[132:133], 0, s[10:11]
	global_load_dwordx2 v[214:215], v[240:241], off
	global_load_dwordx2 v[216:217], v[240:241], off offset:512
	global_load_dwordx2 v[218:219], v[240:241], off offset:1024
	global_load_dwordx2 v[220:221], v[240:241], off offset:1536
	global_load_dwordx2 v[222:223], v[240:241], off offset:2048
	global_load_dwordx2 v[224:225], v[240:241], off offset:2560
	global_load_dwordx2 v[226:227], v[240:241], off offset:3072
	global_load_dwordx2 v[228:229], v[240:241], off offset:3584
	s_mov_b32 s2, 1
	s_branch .Lrp_pfset
